# grid barrier: XCD leader invalidates together with its L2 writeback (all its workgroups already wait), releases locals right after the cross-XCD release
# baseline (speedup 1.0000x reference)
; __device__ __forceinline__ unsigned xb_add(unsigned* p, unsigned v) { return __hip_atomic_fetch_add(p, v, __ATOMIC_RELAXED, __HIP_MEMORY_SCOPE_AGENT); }
; __device__ __forceinline__ void xcd_barrier(const XcdBarrier& b, int wave_id) {
;     ...
;         if (old + 1u == (gen + 1u) * nloc) {
;             __builtin_amdgcn_fence(__ATOMIC_RELEASE, "agent");
;             asm volatile("s_waitcnt vmcnt(0)" ::: "memory");
;             const unsigned og = xb_add(&bar[XB_TOP], 1u);
;             const unsigned tg = og / nx;
;             if (og + 1u == (tg + 1u) * nx) xb_add(&bar[XB_TOPGEN], 1u);
.LBB0_79:
	s_andn2_saveexec_b64 s[8:9], s[8:9]
	s_cbranch_execz .LBB0_99
	s_mov_b64 s[8:9], exec
	buffer_wbl2 sc1
	buffer_inv sc1
	s_waitcnt lgkmcnt(0)
	s_waitcnt vmcnt(0)
	v_mbcnt_lo_u32_b32 v1, s8, 0
	v_mbcnt_hi_u32_b32 v1, s9, v1
	v_cmp_eq_u32_e32 vcc, 0, v1
	s_and_saveexec_b64 s[18:19], vcc
	s_cbranch_execz .LBB0_82
	s_bcnt1_i32_b64 s8, s[8:9]
	v_mov_b32_e32 v2, 0xff43000
	v_mov_b32_e32 v3, s8
	global_atomic_add v2, v2, v3, s[14:15] offset:1024 sc0

; __device__ __forceinline__ unsigned xb_ld(unsigned* p)              { return __hip_atomic_load(p, __ATOMIC_RELAXED, __HIP_MEMORY_SCOPE_AGENT); }
; __device__ __forceinline__ unsigned xb_add(unsigned* p, unsigned v) { return __hip_atomic_fetch_add(p, v, __ATOMIC_RELAXED, __HIP_MEMORY_SCOPE_AGENT); }
; #define XB_SPIN(cond, bar) do { unsigned _sp = 0; while (cond) { __builtin_amdgcn_s_sleep(1); \
;     if ((++_sp & 255u) == 0u) { if (xb_ld(&(bar)[XB_TMO])) break; if (_sp > XB_SPIN_CAP) { atomicAdd(&(bar)[XB_TMO], 1u); break; } } } } while (0)
; __device__ __forceinline__ void xcd_barrier(const XcdBarrier& b, int wave_id) {
;     ...
;             else XB_SPIN(xb_ld(&bar[XB_TOPGEN]) == tg, bar);
;             __builtin_amdgcn_fence(__ATOMIC_ACQUIRE, "agent");
;             xb_add(&bar[XB_XGEN(b.x)], 1u);
;             asm volatile("s_waitcnt vmcnt(0)" ::: "memory");
.LBB0_96:
	s_or_b64 exec, exec, s[8:9]
	s_mov_b64 s[8:9], exec
	v_mbcnt_lo_u32_b32 v0, s8, 0
	v_mbcnt_hi_u32_b32 v0, s9, v0
	v_cmp_eq_u32_e32 vcc, 0, v0
	s_nop 0
	s_nop 0
	s_nop 0
	s_and_saveexec_b64 s[18:19], vcc
	s_cbranch_execz .LBB0_98
	s_bcnt1_i32_b64 s8, s[8:9]
	v_mov_b32_e32 v0, 0x2000
	v_mov_b32_e32 v1, s8
	global_atomic_add v0, v1, s[6:7] offset:1024

; __device__ __forceinline__ unsigned xb_add(unsigned* p, unsigned v) { return __hip_atomic_fetch_add(p, v, __ATOMIC_RELAXED, __HIP_MEMORY_SCOPE_AGENT); }
; __device__ __forceinline__ void xcd_barrier(const XcdBarrier& b, int wave_id) {
;     ...
;         if (old + 1u == (gen + 1u) * nloc) {
;             __builtin_amdgcn_fence(__ATOMIC_RELEASE, "agent");
;             asm volatile("s_waitcnt vmcnt(0)" ::: "memory");
;             const unsigned og = xb_add(&bar[XB_TOP], 1u);
;             const unsigned tg = og / nx;
;             if (og + 1u == (tg + 1u) * nx) xb_add(&bar[XB_TOPGEN], 1u);
.LBB0_239:
	s_andn2_saveexec_b64 s[8:9], s[8:9]
	s_cbranch_execz .LBB0_259
	s_mov_b64 s[8:9], exec
	buffer_wbl2 sc1
	buffer_inv sc1
	s_waitcnt lgkmcnt(0)
	s_waitcnt vmcnt(0)
	v_mbcnt_lo_u32_b32 v1, s8, 0
	v_mbcnt_hi_u32_b32 v1, s9, v1
	v_cmp_eq_u32_e32 vcc, 0, v1
	s_and_saveexec_b64 s[10:11], vcc
	s_cbranch_execz .LBB0_242
	s_bcnt1_i32_b64 s8, s[8:9]
	v_mov_b32_e32 v2, 0xff43000
	v_mov_b32_e32 v3, s8
	global_atomic_add v2, v2, v3, s[14:15] offset:1024 sc0

; __device__ __forceinline__ unsigned xb_ld(unsigned* p)              { return __hip_atomic_load(p, __ATOMIC_RELAXED, __HIP_MEMORY_SCOPE_AGENT); }
; __device__ __forceinline__ unsigned xb_add(unsigned* p, unsigned v) { return __hip_atomic_fetch_add(p, v, __ATOMIC_RELAXED, __HIP_MEMORY_SCOPE_AGENT); }
; #define XB_SPIN(cond, bar) do { unsigned _sp = 0; while (cond) { __builtin_amdgcn_s_sleep(1); \
;     if ((++_sp & 255u) == 0u) { if (xb_ld(&(bar)[XB_TMO])) break; if (_sp > XB_SPIN_CAP) { atomicAdd(&(bar)[XB_TMO], 1u); break; } } } } while (0)
; __device__ __forceinline__ void xcd_barrier(const XcdBarrier& b, int wave_id) {
;     ...
;             else XB_SPIN(xb_ld(&bar[XB_TOPGEN]) == tg, bar);
;             __builtin_amdgcn_fence(__ATOMIC_ACQUIRE, "agent");
;             xb_add(&bar[XB_XGEN(b.x)], 1u);
;             asm volatile("s_waitcnt vmcnt(0)" ::: "memory");
.LBB0_256:
	s_or_b64 exec, exec, s[8:9]
	s_mov_b64 s[8:9], exec
	v_mbcnt_lo_u32_b32 v0, s8, 0
	v_mbcnt_hi_u32_b32 v0, s9, v0
	v_cmp_eq_u32_e32 vcc, 0, v0
	s_nop 0
	s_nop 0
	s_nop 0
	s_and_saveexec_b64 s[10:11], vcc
	s_cbranch_execz .LBB0_258
	s_bcnt1_i32_b64 s8, s[8:9]
	v_mov_b32_e32 v0, 0x2000
	v_mov_b32_e32 v1, s8
	global_atomic_add v0, v1, s[6:7] offset:1024

; __device__ __forceinline__ unsigned xb_add(unsigned* p, unsigned v) { return __hip_atomic_fetch_add(p, v, __ATOMIC_RELAXED, __HIP_MEMORY_SCOPE_AGENT); }
; __device__ __forceinline__ void xcd_barrier(const XcdBarrier& b, int wave_id) {
;     ...
;         const unsigned old = xb_add(&bar[XB_XSUB(b.x)], 1u);
;         const unsigned gen = old / nloc;
;         if (old + 1u == (gen + 1u) * nloc) {
;             __builtin_amdgcn_fence(__ATOMIC_RELEASE, "agent");
;             asm volatile("s_waitcnt vmcnt(0)" ::: "memory");
;             const unsigned og = xb_add(&bar[XB_TOP], 1u);
.LBB0_401:
	s_andn2_saveexec_b64 s[6:7], s[20:21]
	s_cbranch_execz .LBB0_421
	s_mov_b64 s[20:21], exec
	buffer_wbl2 sc1
	buffer_inv sc1
	s_waitcnt lgkmcnt(0)
	s_waitcnt vmcnt(0)
	v_mbcnt_lo_u32_b32 v1, s20, 0
	v_mbcnt_hi_u32_b32 v1, s21, v1
	v_cmp_eq_u32_e32 vcc, 0, v1
	s_and_saveexec_b64 s[22:23], vcc
	s_cbranch_execz .LBB0_404
	s_bcnt1_i32_b64 s6, s[20:21]
	v_mov_b32_e32 v2, 0xff43000
	v_mov_b32_e32 v3, s6
	global_atomic_add v2, v2, v3, s[14:15] offset:1024 sc0

; __device__ __forceinline__ unsigned xb_ld(unsigned* p)              { return __hip_atomic_load(p, __ATOMIC_RELAXED, __HIP_MEMORY_SCOPE_AGENT); }
; __device__ __forceinline__ unsigned xb_add(unsigned* p, unsigned v) { return __hip_atomic_fetch_add(p, v, __ATOMIC_RELAXED, __HIP_MEMORY_SCOPE_AGENT); }
; #define XB_SPIN(cond, bar) do { unsigned _sp = 0; while (cond) { __builtin_amdgcn_s_sleep(1); \
;     if ((++_sp & 255u) == 0u) { if (xb_ld(&(bar)[XB_TMO])) break; if (_sp > XB_SPIN_CAP) { atomicAdd(&(bar)[XB_TMO], 1u); break; } } } } while (0)
; __device__ __forceinline__ void xcd_barrier(const XcdBarrier& b, int wave_id) {
;     ...
;             else XB_SPIN(xb_ld(&bar[XB_TOPGEN]) == tg, bar);
;             __builtin_amdgcn_fence(__ATOMIC_ACQUIRE, "agent");
;             xb_add(&bar[XB_XGEN(b.x)], 1u);
;             asm volatile("s_waitcnt vmcnt(0)" ::: "memory");
.LBB0_418:
	s_or_b64 exec, exec, s[20:21]
	s_mov_b64 s[20:21], exec
	v_mbcnt_lo_u32_b32 v0, s20, 0
	v_mbcnt_hi_u32_b32 v0, s21, v0
	v_cmp_eq_u32_e32 vcc, 0, v0
	s_nop 0
	s_nop 0
	s_nop 0
	s_and_saveexec_b64 s[22:23], vcc
	s_cbranch_execz .LBB0_420
	s_bcnt1_i32_b64 s6, s[20:21]
	v_mov_b32_e32 v0, 0x2000
	v_mov_b32_e32 v1, s6
	global_atomic_add v0, v1, s[10:11] offset:1024

; __device__ __forceinline__ unsigned xb_add(unsigned* p, unsigned v) { return __hip_atomic_fetch_add(p, v, __ATOMIC_RELAXED, __HIP_MEMORY_SCOPE_AGENT); }
; __device__ __forceinline__ void xcd_barrier(const XcdBarrier& b, int wave_id) {
;     ...
;         const unsigned old = xb_add(&bar[XB_XSUB(b.x)], 1u);
;         const unsigned gen = old / nloc;
;         if (old + 1u == (gen + 1u) * nloc) {
;             __builtin_amdgcn_fence(__ATOMIC_RELEASE, "agent");
;             asm volatile("s_waitcnt vmcnt(0)" ::: "memory");
;             const unsigned og = xb_add(&bar[XB_TOP], 1u);
.LBB0_484:
	s_andn2_saveexec_b64 s[6:7], s[10:11]
	s_cbranch_execz .LBB0_504
	s_mov_b64 s[10:11], exec
	buffer_wbl2 sc1
	buffer_inv sc1
	s_waitcnt lgkmcnt(0)
	s_waitcnt vmcnt(0)
	v_mbcnt_lo_u32_b32 v1, s10, 0
	v_mbcnt_hi_u32_b32 v1, s11, v1
	v_cmp_eq_u32_e32 vcc, 0, v1
	s_and_saveexec_b64 s[22:23], vcc
	s_cbranch_execz .LBB0_487
	s_bcnt1_i32_b64 s6, s[10:11]
	v_mov_b32_e32 v2, 0xff43000
	v_mov_b32_e32 v3, s6
	global_atomic_add v2, v2, v3, s[14:15] offset:1024 sc0

; __device__ __forceinline__ unsigned xb_ld(unsigned* p)              { return __hip_atomic_load(p, __ATOMIC_RELAXED, __HIP_MEMORY_SCOPE_AGENT); }
; __device__ __forceinline__ unsigned xb_add(unsigned* p, unsigned v) { return __hip_atomic_fetch_add(p, v, __ATOMIC_RELAXED, __HIP_MEMORY_SCOPE_AGENT); }
; #define XB_SPIN(cond, bar) do { unsigned _sp = 0; while (cond) { __builtin_amdgcn_s_sleep(1); \
;     if ((++_sp & 255u) == 0u) { if (xb_ld(&(bar)[XB_TMO])) break; if (_sp > XB_SPIN_CAP) { atomicAdd(&(bar)[XB_TMO], 1u); break; } } } } while (0)
; __device__ __forceinline__ void xcd_barrier(const XcdBarrier& b, int wave_id) {
;     ...
;             else XB_SPIN(xb_ld(&bar[XB_TOPGEN]) == tg, bar);
;             __builtin_amdgcn_fence(__ATOMIC_ACQUIRE, "agent");
;             xb_add(&bar[XB_XGEN(b.x)], 1u);
;             asm volatile("s_waitcnt vmcnt(0)" ::: "memory");
.LBB0_501:
	s_or_b64 exec, exec, s[10:11]
	s_mov_b64 s[10:11], exec
	v_mbcnt_lo_u32_b32 v0, s10, 0
	v_mbcnt_hi_u32_b32 v0, s11, v0
	v_cmp_eq_u32_e32 vcc, 0, v0
	s_nop 0
	s_nop 0
	s_nop 0
	s_and_saveexec_b64 s[22:23], vcc
	s_cbranch_execz .LBB0_503
	s_bcnt1_i32_b64 s6, s[10:11]
	v_mov_b32_e32 v0, 0x2000
	v_mov_b32_e32 v1, s6
	global_atomic_add v0, v1, s[8:9] offset:1024

; __device__ __forceinline__ unsigned xb_add(unsigned* p, unsigned v) { return __hip_atomic_fetch_add(p, v, __ATOMIC_RELAXED, __HIP_MEMORY_SCOPE_AGENT); }
; __device__ __forceinline__ void xcd_barrier(const XcdBarrier& b, int wave_id) {
;     ...
;         const unsigned old = xb_add(&bar[XB_XSUB(b.x)], 1u);
;         const unsigned gen = old / nloc;
;         if (old + 1u == (gen + 1u) * nloc) {
;             __builtin_amdgcn_fence(__ATOMIC_RELEASE, "agent");
;             asm volatile("s_waitcnt vmcnt(0)" ::: "memory");
;             const unsigned og = xb_add(&bar[XB_TOP], 1u);
.LBB0_592:
	s_andn2_saveexec_b64 s[8:9], s[8:9]
	s_cbranch_execz .LBB0_612
	s_mov_b64 s[8:9], exec
	buffer_wbl2 sc1
	buffer_inv sc1
	s_waitcnt lgkmcnt(0)
	s_waitcnt vmcnt(0)
	v_mbcnt_lo_u32_b32 v1, s8, 0
	v_mbcnt_hi_u32_b32 v1, s9, v1
	v_cmp_eq_u32_e32 vcc, 0, v1
	s_and_saveexec_b64 s[22:23], vcc
	s_cbranch_execz .LBB0_595
	s_bcnt1_i32_b64 s8, s[8:9]
	v_mov_b32_e32 v2, 0xff43000
	v_mov_b32_e32 v3, s8
	global_atomic_add v2, v2, v3, s[14:15] offset:1024 sc0

; __device__ __forceinline__ unsigned xb_ld(unsigned* p)              { return __hip_atomic_load(p, __ATOMIC_RELAXED, __HIP_MEMORY_SCOPE_AGENT); }
; __device__ __forceinline__ unsigned xb_add(unsigned* p, unsigned v) { return __hip_atomic_fetch_add(p, v, __ATOMIC_RELAXED, __HIP_MEMORY_SCOPE_AGENT); }
; #define XB_SPIN(cond, bar) do { unsigned _sp = 0; while (cond) { __builtin_amdgcn_s_sleep(1); \
;     if ((++_sp & 255u) == 0u) { if (xb_ld(&(bar)[XB_TMO])) break; if (_sp > XB_SPIN_CAP) { atomicAdd(&(bar)[XB_TMO], 1u); break; } } } } while (0)
; __device__ __forceinline__ void xcd_barrier(const XcdBarrier& b, int wave_id) {
;     ...
;             else XB_SPIN(xb_ld(&bar[XB_TOPGEN]) == tg, bar);
;             __builtin_amdgcn_fence(__ATOMIC_ACQUIRE, "agent");
;             xb_add(&bar[XB_XGEN(b.x)], 1u);
;             asm volatile("s_waitcnt vmcnt(0)" ::: "memory");
.LBB0_609:
	s_or_b64 exec, exec, s[8:9]
	s_mov_b64 s[8:9], exec
	v_mbcnt_lo_u32_b32 v0, s8, 0
	v_mbcnt_hi_u32_b32 v0, s9, v0
	v_cmp_eq_u32_e32 vcc, 0, v0
	s_nop 0
	s_nop 0
	s_nop 0
	s_and_saveexec_b64 s[22:23], vcc
	s_cbranch_execz .LBB0_611
	s_bcnt1_i32_b64 s8, s[8:9]
	v_mov_b32_e32 v0, 0x2000
	v_mov_b32_e32 v1, s8
	global_atomic_add v0, v1, s[6:7] offset:1024

; __device__ __forceinline__ unsigned xb_add(unsigned* p, unsigned v) { return __hip_atomic_fetch_add(p, v, __ATOMIC_RELAXED, __HIP_MEMORY_SCOPE_AGENT); }
; __device__ __forceinline__ void xcd_barrier(const XcdBarrier& b, int wave_id) {
;     ...
;         const unsigned old = xb_add(&bar[XB_XSUB(b.x)], 1u);
;         const unsigned gen = old / nloc;
;         if (old + 1u == (gen + 1u) * nloc) {
;             __builtin_amdgcn_fence(__ATOMIC_RELEASE, "agent");
;             asm volatile("s_waitcnt vmcnt(0)" ::: "memory");
;             const unsigned og = xb_add(&bar[XB_TOP], 1u);
.LBB0_688:
	s_andn2_saveexec_b64 s[8:9], s[8:9]
	s_cbranch_execz .LBB0_708
	s_mov_b64 s[8:9], exec
	buffer_wbl2 sc1
	buffer_inv sc1
	s_waitcnt lgkmcnt(0)
	s_waitcnt vmcnt(0)
	v_mbcnt_lo_u32_b32 v1, s8, 0
	v_mbcnt_hi_u32_b32 v1, s9, v1
	v_cmp_eq_u32_e32 vcc, 0, v1
	s_and_saveexec_b64 s[16:17], vcc
	s_cbranch_execz .LBB0_691
	s_bcnt1_i32_b64 s8, s[8:9]
	v_mov_b32_e32 v2, 0xff43000
	v_mov_b32_e32 v3, s8
	global_atomic_add v2, v2, v3, s[14:15] offset:1024 sc0

; __device__ __forceinline__ unsigned xb_ld(unsigned* p)              { return __hip_atomic_load(p, __ATOMIC_RELAXED, __HIP_MEMORY_SCOPE_AGENT); }
; __device__ __forceinline__ unsigned xb_add(unsigned* p, unsigned v) { return __hip_atomic_fetch_add(p, v, __ATOMIC_RELAXED, __HIP_MEMORY_SCOPE_AGENT); }
; #define XB_SPIN(cond, bar) do { unsigned _sp = 0; while (cond) { __builtin_amdgcn_s_sleep(1); \
;     if ((++_sp & 255u) == 0u) { if (xb_ld(&(bar)[XB_TMO])) break; if (_sp > XB_SPIN_CAP) { atomicAdd(&(bar)[XB_TMO], 1u); break; } } } } while (0)
; __device__ __forceinline__ void xcd_barrier(const XcdBarrier& b, int wave_id) {
;     ...
;             else XB_SPIN(xb_ld(&bar[XB_TOPGEN]) == tg, bar);
;             __builtin_amdgcn_fence(__ATOMIC_ACQUIRE, "agent");
;             xb_add(&bar[XB_XGEN(b.x)], 1u);
;             asm volatile("s_waitcnt vmcnt(0)" ::: "memory");
.LBB0_705:
	s_or_b64 exec, exec, s[8:9]
	s_mov_b64 s[8:9], exec
	v_mbcnt_lo_u32_b32 v0, s8, 0
	v_mbcnt_hi_u32_b32 v0, s9, v0
	v_cmp_eq_u32_e32 vcc, 0, v0
	s_nop 0
	s_nop 0
	s_nop 0
	s_and_saveexec_b64 s[16:17], vcc
	s_cbranch_execz .LBB0_707
	s_bcnt1_i32_b64 s8, s[8:9]
	v_mov_b32_e32 v0, 0x2000
	v_mov_b32_e32 v1, s8
	global_atomic_add v0, v1, s[6:7] offset:1024

; __device__ __forceinline__ unsigned xb_add(unsigned* p, unsigned v) { return __hip_atomic_fetch_add(p, v, __ATOMIC_RELAXED, __HIP_MEMORY_SCOPE_AGENT); }
; __device__ __forceinline__ void xcd_barrier(const XcdBarrier& b, int wave_id) {
;     ...
;         const unsigned old = xb_add(&bar[XB_XSUB(b.x)], 1u);
;         const unsigned gen = old / nloc;
;         if (old + 1u == (gen + 1u) * nloc) {
;             __builtin_amdgcn_fence(__ATOMIC_RELEASE, "agent");
;             asm volatile("s_waitcnt vmcnt(0)" ::: "memory");
;             const unsigned og = xb_add(&bar[XB_TOP], 1u);
.LBB0_764:
	s_andn2_saveexec_b64 s[16:17], s[16:17]
	s_cbranch_execz .LBB0_784
	s_mov_b64 s[16:17], exec
	buffer_wbl2 sc1
	buffer_inv sc1
	s_waitcnt lgkmcnt(0)
	s_waitcnt vmcnt(0)
	v_mbcnt_lo_u32_b32 v1, s16, 0
	v_mbcnt_hi_u32_b32 v1, s17, v1
	v_cmp_eq_u32_e32 vcc, 0, v1
	s_and_saveexec_b64 s[18:19], vcc
	s_cbranch_execz .LBB0_767
	s_bcnt1_i32_b64 s3, s[16:17]
	v_mov_b32_e32 v2, 0xff43000
	v_mov_b32_e32 v3, s3
	global_atomic_add v2, v2, v3, s[14:15] offset:1024 sc0

; __device__ __forceinline__ unsigned xb_ld(unsigned* p)              { return __hip_atomic_load(p, __ATOMIC_RELAXED, __HIP_MEMORY_SCOPE_AGENT); }
; __device__ __forceinline__ unsigned xb_add(unsigned* p, unsigned v) { return __hip_atomic_fetch_add(p, v, __ATOMIC_RELAXED, __HIP_MEMORY_SCOPE_AGENT); }
; #define XB_SPIN(cond, bar) do { unsigned _sp = 0; while (cond) { __builtin_amdgcn_s_sleep(1); \
;     if ((++_sp & 255u) == 0u) { if (xb_ld(&(bar)[XB_TMO])) break; if (_sp > XB_SPIN_CAP) { atomicAdd(&(bar)[XB_TMO], 1u); break; } } } } while (0)
; __device__ __forceinline__ void xcd_barrier(const XcdBarrier& b, int wave_id) {
;     ...
;             else XB_SPIN(xb_ld(&bar[XB_TOPGEN]) == tg, bar);
;             __builtin_amdgcn_fence(__ATOMIC_ACQUIRE, "agent");
;             xb_add(&bar[XB_XGEN(b.x)], 1u);
;             asm volatile("s_waitcnt vmcnt(0)" ::: "memory");
.LBB0_781:
	s_or_b64 exec, exec, s[14:15]
	s_mov_b64 s[14:15], exec
	v_mbcnt_lo_u32_b32 v0, s14, 0
	v_mbcnt_hi_u32_b32 v0, s15, v0
	v_cmp_eq_u32_e32 vcc, 0, v0
	s_nop 0
	s_nop 0
	s_nop 0
	s_and_saveexec_b64 s[16:17], vcc
	s_cbranch_execz .LBB0_783
	s_bcnt1_i32_b64 s3, s[14:15]
	v_mov_b32_e32 v0, 0x2000
	v_mov_b32_e32 v1, s3
	global_atomic_add v0, v1, s[4:5] offset:1024
